# v21 + windowed D loop: first QK MFMA waits only for its own K fragment (lgkmcnt 7) instead of a full LDS drain
# speedup vs baseline: 1.0254x; 1.0001x over previous
; #define LAS __attribute__((address_space(3)))
; DI s16x4 vtr(const LAS unsigned char* p) { return __builtin_bit_cast(s16x4, __builtin_amdgcn_ds_read_tr16_b64_v4i16((LAS s16x4*)p)); }
; template <int DQK, bool WIN>
; DI void attn_run(int wv, const bf16_t* Qrow0, int qs, const bf16_t* Kb, int ks, const bf16_t* Vb, int vs,
;                  int kt0, int kt1, int qpos0, int window, LAS unsigned char* lds, f32x16 (&o)[2], float& m_out, float& l_out) {
;     ...
;         if (WIN) need = (64 * kt + 63 >= qpos0 - window) && (64 * kt <= qpos0 + 31 + window);
;         if (need) {
;             const LAS unsigned char* base = lds + buf * BUF;
;             bf16x8 kf0[NDS], kf1[NDS];
; #pragma unroll
;             for (int ds = 0; ds < NDS; ++ds) {
;                 kf0[ds] = *(const LAS bf16x8*)(base + kfo + ds * 32);
;                 kf1[ds] = *(const LAS bf16x8*)(base + kfo + 32 * KP + ds * 32);
;             }
;             __builtin_amdgcn_s_setprio(1);
;             f32x16 p0 = __builtin_amdgcn_mfma_f32_32x32x16_bf16(kf0[0], q[0], negm, 0, 0, 0);
;             f32x16 p1 = __builtin_amdgcn_mfma_f32_32x32x16_bf16(kf1[0], q[0], negm, 0, 0, 0);
; #pragma unroll
;             for (int ds = 1; ds < NDS; ++ds) {
;                 p0 = __builtin_amdgcn_mfma_f32_32x32x16_bf16(kf0[ds], q[ds], p0, 0, 0, 0);
;                 p1 = __builtin_amdgcn_mfma_f32_32x32x16_bf16(kf1[ds], q[ds], p1, 0, 0, 0);
;             }
;             __builtin_amdgcn_s_setprio(0);
;             s16x4 vlo[4][2], vhi[4][2];
; #pragma unroll
;             for (int k4 = 0; k4 < 4; ++k4)
; #pragma unroll
;                 for (int db = 0; db < 2; ++db) {
;                     vlo[k4][db] = vtr(base + vfo + (16 * k4) * VP + 64 * db);
;                     vhi[k4][db] = vtr(base + vfo + (16 * k4 + 8) * VP + 64 * db);
;                 }
.Lew_d_skip:
	s_sub_i32 s28, s26, 64
	s_add_i32 s26, s26, -1
	s_cmp_ge_i32 s26, s34
	s_cselect_b64 s[26:27], -1, 0
	s_cmp_le_i32 s28, s35
	s_cselect_b64 s[28:29], -1, 0
	s_and_b64 s[26:27], s[26:27], s[28:29]
	s_andn2_b64 vcc, exec, s[26:27]
	s_cbranch_vccnz .LBB0_1255
	s_mul_i32 s26, s15, 0x5400
	s_add_i32 s28, s26, 0
	v_add3_u32 v52, s28, v154, v144
	ds_read_b128 v[48:51], v52
	ds_read_b128 v[112:115], v52 offset:32
	ds_read_b128 v[116:119], v52 offset:4608
	ds_read_b128 v[120:123], v52 offset:4640
	ds_read_b128 v[124:127], v52 offset:64
	ds_read_b128 v[146:149], v52 offset:96
	ds_read_b128 v[162:165], v52 offset:4672
	ds_read_b128 v[166:169], v52 offset:4704
	s_xor_b64 s[26:27], s[24:25], -1
	s_setprio 1
	s_waitcnt lgkmcnt(7)
	v_mfma_f32_32x32x16_bf16 v[64:79], v[48:51], v[80:83], v[32:47]
	s_waitcnt lgkmcnt(5)
	v_mfma_f32_32x32x16_bf16 v[48:63], v[116:119], v[80:83], v[32:47]
	s_setprio 0
	v_mfma_f32_32x32x16_bf16 v[64:79], v[112:115], v[84:87], v[64:79]
	v_add_u32_e32 v112, s28, v156
	s_waitcnt lgkmcnt(4)
	v_mfma_f32_32x32x16_bf16 v[48:63], v[120:123], v[84:87], v[48:63]
	v_add3_u32 v152, v112, v155, v157
	ds_read_b64_tr_b16 v[132:133], v152 offset:9216
	ds_read_b64_tr_b16 v[134:135], v152 offset:10752
	ds_read_b64_tr_b16 v[130:131], v152 offset:10816
	ds_read_b64_tr_b16 v[128:129], v152 offset:9280
	s_waitcnt lgkmcnt(7)
	v_mfma_f32_32x32x16_bf16 v[64:79], v[124:127], v[88:91], v[64:79]
	ds_read_b64_tr_b16 v[124:125], v152 offset:12288
	ds_read_b64_tr_b16 v[126:127], v152 offset:13824
	ds_read_b64_tr_b16 v[122:123], v152 offset:13888
	ds_read_b64_tr_b16 v[120:121], v152 offset:12352
	ds_read_b64_tr_b16 v[116:117], v152 offset:15360
	ds_read_b64_tr_b16 v[118:119], v152 offset:16896
	ds_read_b64_tr_b16 v[114:115], v152 offset:16960
	ds_read_b64_tr_b16 v[112:113], v152 offset:15424
	s_waitcnt lgkmcnt(13)
	v_mfma_f32_32x32x16_bf16 v[48:63], v[162:165], v[88:91], v[48:63]
	v_mfma_f32_32x32x16_bf16 v[64:79], v[146:149], v[92:95], v[64:79]
	s_waitcnt lgkmcnt(12)
	v_mfma_f32_32x32x16_bf16 v[48:63], v[166:169], v[92:95], v[48:63]
	s_cmp_eq_u32 m0, 1
	s_cbranch_scc0 .Lwd_slow
	s_nop 7
	v_mov_b32_e32 v142, v64
	s_nop 0
	v_mov_b32_e32 v64, v48
	v_mov_b32_e32 v143, v65
	v_mov_b32_e32 v65, v49
	v_mov_b32_e32 v146, v66
	v_mov_b32_e32 v66, v50
	v_mov_b32_e32 v147, v67
	v_mov_b32_e32 v67, v51
	v_mov_b32_e32 v148, v68
	v_mov_b32_e32 v68, v52
	v_mov_b32_e32 v149, v69
	v_mov_b32_e32 v69, v53
	v_mov_b32_e32 v150, v70
	v_mov_b32_e32 v70, v54
	v_mov_b32_e32 v151, v71
	v_mov_b32_e32 v71, v55
	s_branch .Lwd_join
